# v4 + 128B-aligned lean K-loops + P5 merge-epilogue gate loads hoisted (12 round trips to 1)
# baseline (speedup 1.0000x reference)
.LBB0_156:
	s_ashr_i32 s65, s64, 31
	s_lshl_b64 s[34:35], s[64:65], 20
	s_add_u32 s66, s33, s34
	s_addc_u32 s67, s38, s35
	s_and_b64 s[34:35], s[72:73], exec
	s_cselect_b32 s2, s67, s9
	s_cselect_b32 s13, s66, s8
	s_ashr_i32 s63, s62, 31
	s_lshl_b64 s[34:35], s[62:63], 20
	s_add_u32 s68, s36, s34
	s_addc_u32 s69, s37, s35
	s_and_b64 s[34:35], s[72:73], exec
	s_cselect_b32 s20, s69, s11
	s_cselect_b32 s63, s68, s10
	s_add_u32 s8, s8, 0x80080
	s_addc_u32 s9, s9, 0
	s_add_u32 s65, s10, 0x100
	v_mov_b32_e32 v0, 0
	s_addc_u32 s71, s11, 0
	s_mov_b32 s74, -2
	v_mov_b32_e32 v1, v0
	v_mov_b32_e32 v2, v0
	v_mov_b32_e32 v3, v0
	v_mov_b32_e32 v4, v0
	v_mov_b32_e32 v5, v0
	v_mov_b32_e32 v6, v0
	v_mov_b32_e32 v7, v0
	v_mov_b32_e32 v16, v0
	v_mov_b32_e32 v17, v0
	v_mov_b32_e32 v18, v0
	v_mov_b32_e32 v19, v0
	v_mov_b32_e32 v20, v0
	v_mov_b32_e32 v21, v0
	v_mov_b32_e32 v22, v0
	v_mov_b32_e32 v23, v0
	v_mov_b32_e32 v32, v0
	v_mov_b32_e32 v33, v0
	v_mov_b32_e32 v34, v0
	v_mov_b32_e32 v35, v0
	v_mov_b32_e32 v36, v0
	v_mov_b32_e32 v37, v0
	v_mov_b32_e32 v38, v0
	v_mov_b32_e32 v39, v0
	v_mov_b32_e32 v48, v0
	v_mov_b32_e32 v49, v0
	v_mov_b32_e32 v50, v0
	v_mov_b32_e32 v51, v0
	v_mov_b32_e32 v52, v0
	v_mov_b32_e32 v53, v0
	v_mov_b32_e32 v54, v0
	v_mov_b32_e32 v55, v0
	v_mov_b32_e32 v8, v0
	v_mov_b32_e32 v9, v0
	v_mov_b32_e32 v10, v0
	v_mov_b32_e32 v11, v0
	v_mov_b32_e32 v12, v0
	v_mov_b32_e32 v13, v0
	v_mov_b32_e32 v14, v0
	v_mov_b32_e32 v15, v0
	v_mov_b32_e32 v24, v0
	v_mov_b32_e32 v25, v0
	v_mov_b32_e32 v26, v0
	v_mov_b32_e32 v27, v0
	v_mov_b32_e32 v28, v0
	v_mov_b32_e32 v29, v0
	v_mov_b32_e32 v30, v0
	v_mov_b32_e32 v31, v0
	v_mov_b32_e32 v40, v0
	v_mov_b32_e32 v41, v0
	v_mov_b32_e32 v42, v0
	v_mov_b32_e32 v43, v0
	v_mov_b32_e32 v44, v0
	v_mov_b32_e32 v45, v0
	v_mov_b32_e32 v46, v0
	v_mov_b32_e32 v47, v0
	v_mov_b32_e32 v56, v0
	v_mov_b32_e32 v57, v0
	v_mov_b32_e32 v58, v0
	v_mov_b32_e32 v59, v0
	v_mov_b32_e32 v60, v0
	v_mov_b32_e32 v61, v0
	v_mov_b32_e32 v62, v0
	v_mov_b32_e32 v63, v0
	v_mov_b32_e32 v64, v0
	v_mov_b32_e32 v65, v0
	v_mov_b32_e32 v66, v0
	v_mov_b32_e32 v67, v0
	v_mov_b32_e32 v68, v0
	v_mov_b32_e32 v69, v0
	v_mov_b32_e32 v70, v0
	v_mov_b32_e32 v71, v0
	v_mov_b32_e32 v80, v0
	v_mov_b32_e32 v81, v0
	v_mov_b32_e32 v82, v0
	v_mov_b32_e32 v83, v0
	v_mov_b32_e32 v84, v0
	v_mov_b32_e32 v85, v0
	v_mov_b32_e32 v86, v0
	v_mov_b32_e32 v87, v0
	v_mov_b32_e32 v96, v0
	v_mov_b32_e32 v97, v0
	v_mov_b32_e32 v98, v0
	v_mov_b32_e32 v99, v0
	v_mov_b32_e32 v100, v0
	v_mov_b32_e32 v101, v0
	v_mov_b32_e32 v102, v0
	v_mov_b32_e32 v103, v0
	v_mov_b32_e32 v112, v0
	v_mov_b32_e32 v113, v0
	v_mov_b32_e32 v114, v0
	v_mov_b32_e32 v115, v0
	v_mov_b32_e32 v116, v0
	v_mov_b32_e32 v117, v0
	v_mov_b32_e32 v118, v0
	v_mov_b32_e32 v119, v0
	v_mov_b32_e32 v72, v0
	v_mov_b32_e32 v73, v0
	v_mov_b32_e32 v74, v0
	v_mov_b32_e32 v75, v0
	v_mov_b32_e32 v76, v0
	v_mov_b32_e32 v77, v0
	v_mov_b32_e32 v78, v0
	v_mov_b32_e32 v79, v0
	v_mov_b32_e32 v88, v0
	v_mov_b32_e32 v89, v0
	v_mov_b32_e32 v90, v0
	v_mov_b32_e32 v91, v0
	v_mov_b32_e32 v92, v0
	v_mov_b32_e32 v93, v0
	v_mov_b32_e32 v94, v0
	v_mov_b32_e32 v95, v0
	v_mov_b32_e32 v104, v0
	v_mov_b32_e32 v105, v0
	v_mov_b32_e32 v106, v0
	v_mov_b32_e32 v107, v0
	v_mov_b32_e32 v108, v0
	v_mov_b32_e32 v109, v0
	v_mov_b32_e32 v110, v0
	v_mov_b32_e32 v111, v0
	v_mov_b32_e32 v120, v0
	v_mov_b32_e32 v121, v0
	v_mov_b32_e32 v122, v0
	v_mov_b32_e32 v123, v0
	v_mov_b32_e32 v124, v0
	v_mov_b32_e32 v125, v0
	v_mov_b32_e32 v126, v0
	v_mov_b32_e32 v127, v0
	.p2align 7

.LBB0_845:
	s_mul_i32 s23, s64, 0xc0
	v_add_u32_e32 v2, s23, v165
	v_ashrrev_i32_e32 v3, 31, v2
	s_lshl_b32 s30, s6, 8
	v_lshlrev_b64 v[2:3], 11, v[2:3]
	s_ashr_i32 s31, s30, 31
	v_lshl_add_u64 v[2:3], v[2:3], 0, s[30:31]
	v_or_b32_e32 v2, v2, v164
	v_cndmask_b32_e64 v1, 0, 1, s[18:19]
	v_lshlrev_b64 v[108:109], 1, v[2:3]
	v_add_u32_e32 v118, s23, v180
	v_add_u32_e32 v122, s23, v181
	v_add_u32_e32 v120, s23, v182
	v_add_u32_e32 v2, s23, v183
	s_mov_b64 s[46:47], -1
	v_cmp_ne_u32_e64 s[6:7], 1, v1
	s_andn2_b64 vcc, exec, s[18:19]
	v_lshl_add_u64 v[100:101], s[14:15], 0, v[108:109]
	v_or_b32_e32 v110, 0x100, v108
	v_ashrrev_i32_e32 v119, 31, v118
	v_ashrrev_i32_e32 v123, 31, v122
	v_ashrrev_i32_e32 v121, 31, v120
	v_ashrrev_i32_e32 v3, 31, v2
	v_add_u32_e32 v116, s23, v186
	s_cbranch_vccnz .LBB0_848
	global_load_dwordx4 v[192:195], v[100:101], off
	global_load_dwordx4 v[196:199], v[100:101], off offset:256
	v_ashrrev_i32_e32 v117, 31, v116
	v_lshlrev_b64 v[240:241], 11, v[118:119]
	v_lshl_add_u64 v[240:241], v[240:241], 0, s[30:31]
	v_or_b32_e32 v240, v240, v164
	v_lshlrev_b64 v[240:241], 1, v[240:241]
	v_lshl_add_u64 v[240:241], s[14:15], 0, v[240:241]
	global_load_dwordx4 v[200:203], v[240:241], off
	global_load_dwordx4 v[204:207], v[240:241], off offset:256
	v_lshlrev_b64 v[242:243], 11, v[122:123]
	v_lshl_add_u64 v[242:243], v[242:243], 0, s[30:31]
	v_or_b32_e32 v242, v242, v164
	v_lshlrev_b64 v[242:243], 1, v[242:243]
	v_lshl_add_u64 v[242:243], s[14:15], 0, v[242:243]
	global_load_dwordx4 v[208:211], v[242:243], off
	global_load_dwordx4 v[212:215], v[242:243], off offset:256
	v_lshlrev_b64 v[244:245], 11, v[120:121]
	v_lshl_add_u64 v[244:245], v[244:245], 0, s[30:31]
	v_or_b32_e32 v244, v244, v164
	v_lshlrev_b64 v[244:245], 1, v[244:245]
	v_lshl_add_u64 v[244:245], s[14:15], 0, v[244:245]
	global_load_dwordx4 v[216:219], v[244:245], off
	global_load_dwordx4 v[220:223], v[244:245], off offset:256
	v_lshlrev_b64 v[246:247], 11, v[2:3]
	v_lshl_add_u64 v[246:247], v[246:247], 0, s[30:31]
	v_or_b32_e32 v246, v246, v164
	v_lshlrev_b64 v[246:247], 1, v[246:247]
	v_lshl_add_u64 v[246:247], s[14:15], 0, v[246:247]
	global_load_dwordx4 v[224:227], v[246:247], off
	global_load_dwordx4 v[228:231], v[246:247], off offset:256
	v_lshlrev_b64 v[248:249], 11, v[116:117]
	v_lshl_add_u64 v[248:249], v[248:249], 0, s[30:31]
	v_or_b32_e32 v248, v248, v164
	v_lshlrev_b64 v[248:249], 1, v[248:249]
	v_lshl_add_u64 v[248:249], s[14:15], 0, v[248:249]
	global_load_dwordx4 v[232:235], v[248:249], off
	global_load_dwordx4 v[236:239], v[248:249], off offset:256
	v_mov_b32_e32 v111, v109
	v_lshl_add_u64 v[106:107], s[14:15], 0, v[110:111]
	v_lshl_add_u64 v[126:127], s[16:17], 0, v[110:111]
	v_ashrrev_i32_e32 v117, 31, v116
	s_waitcnt vmcnt(11)
	v_lshlrev_b32_e32 v112, 16, v192
	v_and_b32_e32 v113, 0xffff0000, v192
	v_lshlrev_b32_e32 v102, 16, v193
	v_and_b32_e32 v103, 0xffff0000, v193
	v_lshlrev_b32_e32 v114, 16, v194
	v_and_b32_e32 v115, 0xffff0000, v194
	v_lshlrev_b32_e32 v104, 16, v195
	v_and_b32_e32 v105, 0xffff0000, v195
	v_pk_mul_f32 v[124:125], v[98:99], v[102:103]
	v_pk_mul_f32 v[102:103], v[96:97], v[112:113]
	v_pk_mul_f32 v[112:113], v[94:95], v[104:105]
	v_pk_mul_f32 v[104:105], v[92:93], v[114:115]
	v_cvt_pk_bf16_f32 v102, v102, v103
	v_cvt_pk_bf16_f32 v103, v124, v125
	v_lshlrev_b64 v[124:125], 11, v[118:119]
	v_cvt_pk_bf16_f32 v104, v104, v105
	v_cvt_pk_bf16_f32 v105, v112, v113
	v_lshl_add_u64 v[106:107], s[16:17], 0, v[108:109]
	v_lshl_add_u64 v[124:125], v[124:125], 0, s[30:31]
	v_or_b32_e32 v124, v124, v164
	global_store_dwordx4 v[106:107], v[102:105], off
	v_lshlrev_b64 v[124:125], 1, v[124:125]
	v_lshl_add_u64 v[128:129], s[14:15], 0, v[124:125]
	s_waitcnt vmcnt(11)
	v_lshlrev_b32_e32 v102, 16, v196
	v_and_b32_e32 v103, 0xffff0000, v196
	v_lshlrev_b32_e32 v104, 16, v197
	v_and_b32_e32 v105, 0xffff0000, v197
	v_lshlrev_b32_e32 v106, 16, v198
	v_and_b32_e32 v107, 0xffff0000, v198
	v_lshlrev_b32_e32 v112, 16, v199
	v_and_b32_e32 v113, 0xffff0000, v199
	v_pk_mul_f32 v[104:105], v[74:75], v[104:105]
	v_pk_mul_f32 v[102:103], v[72:73], v[102:103]
	v_pk_mul_f32 v[112:113], v[70:71], v[112:113]
	v_pk_mul_f32 v[106:107], v[68:69], v[106:107]
	v_cvt_pk_bf16_f32 v102, v102, v103
	v_cvt_pk_bf16_f32 v103, v104, v105
	s_nop 0
	v_cvt_pk_bf16_f32 v104, v106, v107
	v_cvt_pk_bf16_f32 v105, v112, v113
	global_store_dwordx4 v[126:127], v[102:105], off
	v_lshl_add_u64 v[106:107], s[16:17], 0, v[124:125]
	v_or_b32_e32 v124, 0x100, v124
	v_lshl_add_u64 v[112:113], s[14:15], 0, v[124:125]
	v_lshl_add_u64 v[124:125], s[16:17], 0, v[124:125]
	s_waitcnt vmcnt(11)
	v_lshlrev_b32_e32 v114, 16, v200
	v_and_b32_e32 v115, 0xffff0000, v200
	v_lshlrev_b32_e32 v102, 16, v201
	v_and_b32_e32 v103, 0xffff0000, v201
	v_lshlrev_b32_e32 v126, 16, v202
	v_and_b32_e32 v127, 0xffff0000, v202
	v_lshlrev_b32_e32 v104, 16, v203
	v_and_b32_e32 v105, 0xffff0000, v203
	v_pk_mul_f32 v[128:129], v[90:91], v[102:103]
	v_pk_mul_f32 v[102:103], v[88:89], v[114:115]
	v_pk_mul_f32 v[114:115], v[86:87], v[104:105]
	v_pk_mul_f32 v[104:105], v[84:85], v[126:127]
	v_cvt_pk_bf16_f32 v102, v102, v103
	v_cvt_pk_bf16_f32 v103, v128, v129
	v_lshlrev_b64 v[126:127], 11, v[122:123]
	v_cvt_pk_bf16_f32 v104, v104, v105
	v_cvt_pk_bf16_f32 v105, v114, v115
	v_lshl_add_u64 v[126:127], v[126:127], 0, s[30:31]
	v_or_b32_e32 v126, v126, v164
	global_store_dwordx4 v[106:107], v[102:105], off
	v_lshlrev_b64 v[126:127], 1, v[126:127]
	v_lshl_add_u64 v[128:129], s[14:15], 0, v[126:127]
	s_waitcnt vmcnt(11)
	v_lshlrev_b32_e32 v102, 16, v204
	v_and_b32_e32 v103, 0xffff0000, v204
	v_lshlrev_b32_e32 v104, 16, v205
	v_and_b32_e32 v105, 0xffff0000, v205
	v_lshlrev_b32_e32 v106, 16, v206
	v_and_b32_e32 v107, 0xffff0000, v206
	v_lshlrev_b32_e32 v112, 16, v207
	v_and_b32_e32 v113, 0xffff0000, v207
	v_pk_mul_f32 v[104:105], v[66:67], v[104:105]
	v_pk_mul_f32 v[102:103], v[64:65], v[102:103]
	v_pk_mul_f32 v[112:113], v[62:63], v[112:113]
	v_pk_mul_f32 v[106:107], v[60:61], v[106:107]
	v_cvt_pk_bf16_f32 v102, v102, v103
	v_cvt_pk_bf16_f32 v103, v104, v105
	s_nop 0
	v_cvt_pk_bf16_f32 v104, v106, v107
	v_cvt_pk_bf16_f32 v105, v112, v113
	global_store_dwordx4 v[124:125], v[102:105], off
	v_lshl_add_u64 v[106:107], s[16:17], 0, v[126:127]
	v_or_b32_e32 v126, 0x100, v126
	v_lshl_add_u64 v[112:113], s[14:15], 0, v[126:127]
	v_lshl_add_u64 v[126:127], s[16:17], 0, v[126:127]
	s_waitcnt vmcnt(11)
	v_lshlrev_b32_e32 v114, 16, v208
	v_and_b32_e32 v115, 0xffff0000, v208
	v_lshlrev_b32_e32 v102, 16, v209
	v_and_b32_e32 v103, 0xffff0000, v209
	v_lshlrev_b32_e32 v124, 16, v210
	v_and_b32_e32 v125, 0xffff0000, v210
	v_lshlrev_b32_e32 v104, 16, v211
	v_and_b32_e32 v105, 0xffff0000, v211
	v_pk_mul_f32 v[128:129], v[82:83], v[102:103]
	v_pk_mul_f32 v[102:103], v[80:81], v[114:115]
	v_pk_mul_f32 v[114:115], v[78:79], v[104:105]
	v_pk_mul_f32 v[104:105], v[76:77], v[124:125]
	v_cvt_pk_bf16_f32 v102, v102, v103
	v_cvt_pk_bf16_f32 v103, v128, v129
	v_lshlrev_b64 v[124:125], 11, v[120:121]
	v_cvt_pk_bf16_f32 v104, v104, v105
	v_cvt_pk_bf16_f32 v105, v114, v115
	v_lshl_add_u64 v[124:125], v[124:125], 0, s[30:31]
	v_or_b32_e32 v124, v124, v164
	global_store_dwordx4 v[106:107], v[102:105], off
	v_lshlrev_b64 v[124:125], 1, v[124:125]
	v_lshl_add_u64 v[128:129], s[14:15], 0, v[124:125]
	s_waitcnt vmcnt(11)
	v_lshlrev_b32_e32 v102, 16, v212
	v_and_b32_e32 v103, 0xffff0000, v212
	v_lshlrev_b32_e32 v104, 16, v213
	v_and_b32_e32 v105, 0xffff0000, v213
	v_lshlrev_b32_e32 v106, 16, v214
	v_and_b32_e32 v107, 0xffff0000, v214
	v_lshlrev_b32_e32 v112, 16, v215
	v_and_b32_e32 v113, 0xffff0000, v215
	v_pk_mul_f32 v[104:105], v[58:59], v[104:105]
	v_pk_mul_f32 v[102:103], v[56:57], v[102:103]
	v_pk_mul_f32 v[112:113], v[54:55], v[112:113]
	v_pk_mul_f32 v[106:107], v[52:53], v[106:107]
	v_cvt_pk_bf16_f32 v102, v102, v103
	v_cvt_pk_bf16_f32 v103, v104, v105
	s_nop 0
	v_cvt_pk_bf16_f32 v104, v106, v107
	v_cvt_pk_bf16_f32 v105, v112, v113
	global_store_dwordx4 v[126:127], v[102:105], off
	v_lshl_add_u64 v[106:107], s[16:17], 0, v[124:125]
	v_or_b32_e32 v124, 0x100, v124
	v_lshl_add_u64 v[112:113], s[14:15], 0, v[124:125]
	v_lshl_add_u64 v[124:125], s[16:17], 0, v[124:125]
	s_waitcnt vmcnt(11)
	v_lshlrev_b32_e32 v114, 16, v216
	v_and_b32_e32 v115, 0xffff0000, v216
	v_lshlrev_b32_e32 v102, 16, v217
	v_and_b32_e32 v103, 0xffff0000, v217
	v_lshlrev_b32_e32 v126, 16, v218
	v_and_b32_e32 v127, 0xffff0000, v218
	v_lshlrev_b32_e32 v104, 16, v219
	v_and_b32_e32 v105, 0xffff0000, v219
	v_pk_mul_f32 v[128:129], v[50:51], v[102:103]
	v_pk_mul_f32 v[102:103], v[48:49], v[114:115]
	v_pk_mul_f32 v[114:115], v[46:47], v[104:105]
	v_pk_mul_f32 v[104:105], v[44:45], v[126:127]
	v_cvt_pk_bf16_f32 v102, v102, v103
	v_cvt_pk_bf16_f32 v103, v128, v129
	v_lshlrev_b64 v[126:127], 11, v[2:3]
	v_cvt_pk_bf16_f32 v104, v104, v105
	v_cvt_pk_bf16_f32 v105, v114, v115
	v_lshl_add_u64 v[126:127], v[126:127], 0, s[30:31]
	v_or_b32_e32 v126, v126, v164
	global_store_dwordx4 v[106:107], v[102:105], off
	v_lshlrev_b64 v[126:127], 1, v[126:127]
	v_lshl_add_u64 v[128:129], s[14:15], 0, v[126:127]
	s_waitcnt vmcnt(11)
	v_lshlrev_b32_e32 v102, 16, v220
	v_and_b32_e32 v103, 0xffff0000, v220
	v_lshlrev_b32_e32 v104, 16, v221
	v_and_b32_e32 v105, 0xffff0000, v221
	v_lshlrev_b32_e32 v106, 16, v222
	v_and_b32_e32 v107, 0xffff0000, v222
	v_lshlrev_b32_e32 v112, 16, v223
	v_and_b32_e32 v113, 0xffff0000, v223
	v_pk_mul_f32 v[104:105], v[26:27], v[104:105]
	v_pk_mul_f32 v[102:103], v[24:25], v[102:103]
	v_pk_mul_f32 v[112:113], v[22:23], v[112:113]
	v_pk_mul_f32 v[106:107], v[20:21], v[106:107]
	v_cvt_pk_bf16_f32 v102, v102, v103
	v_cvt_pk_bf16_f32 v103, v104, v105
	s_nop 0
	v_cvt_pk_bf16_f32 v104, v106, v107
	v_cvt_pk_bf16_f32 v105, v112, v113
	global_store_dwordx4 v[124:125], v[102:105], off
	v_lshl_add_u64 v[106:107], s[16:17], 0, v[126:127]
	v_or_b32_e32 v126, 0x100, v126
	v_lshl_add_u64 v[112:113], s[14:15], 0, v[126:127]
	v_lshl_add_u64 v[126:127], s[16:17], 0, v[126:127]
	s_waitcnt vmcnt(11)
	v_lshlrev_b32_e32 v114, 16, v224
	v_and_b32_e32 v115, 0xffff0000, v224
	v_lshlrev_b32_e32 v102, 16, v225
	v_and_b32_e32 v103, 0xffff0000, v225
	v_lshlrev_b32_e32 v124, 16, v226
	v_and_b32_e32 v125, 0xffff0000, v226
	v_lshlrev_b32_e32 v104, 16, v227
	v_and_b32_e32 v105, 0xffff0000, v227
	v_pk_mul_f32 v[128:129], v[42:43], v[102:103]
	v_pk_mul_f32 v[102:103], v[40:41], v[114:115]
	v_pk_mul_f32 v[114:115], v[38:39], v[104:105]
	v_pk_mul_f32 v[104:105], v[36:37], v[124:125]
	v_cvt_pk_bf16_f32 v102, v102, v103
	v_cvt_pk_bf16_f32 v103, v128, v129
	v_lshlrev_b64 v[124:125], 11, v[116:117]
	v_cvt_pk_bf16_f32 v104, v104, v105
	v_cvt_pk_bf16_f32 v105, v114, v115
	v_lshl_add_u64 v[124:125], v[124:125], 0, s[30:31]
	v_or_b32_e32 v124, v124, v164
	global_store_dwordx4 v[106:107], v[102:105], off
	v_lshlrev_b64 v[124:125], 1, v[124:125]
	v_lshl_add_u64 v[128:129], s[14:15], 0, v[124:125]
	s_waitcnt vmcnt(11)
	v_lshlrev_b32_e32 v102, 16, v228
	v_and_b32_e32 v103, 0xffff0000, v228
	v_lshlrev_b32_e32 v104, 16, v229
	v_and_b32_e32 v105, 0xffff0000, v229
	v_lshlrev_b32_e32 v106, 16, v230
	v_and_b32_e32 v107, 0xffff0000, v230
	v_lshlrev_b32_e32 v112, 16, v231
	v_and_b32_e32 v113, 0xffff0000, v231
	v_pk_mul_f32 v[104:105], v[18:19], v[104:105]
	v_pk_mul_f32 v[102:103], v[16:17], v[102:103]
	v_pk_mul_f32 v[112:113], v[14:15], v[112:113]
	v_pk_mul_f32 v[106:107], v[12:13], v[106:107]
	v_cvt_pk_bf16_f32 v102, v102, v103
	v_cvt_pk_bf16_f32 v103, v104, v105
	s_nop 0
	v_cvt_pk_bf16_f32 v104, v106, v107
	v_cvt_pk_bf16_f32 v105, v112, v113
	global_store_dwordx4 v[126:127], v[102:105], off
	v_lshl_add_u64 v[106:107], s[16:17], 0, v[124:125]
	v_or_b32_e32 v124, 0x100, v124
	v_lshl_add_u64 v[112:113], s[14:15], 0, v[124:125]
	v_lshl_add_u64 v[124:125], s[16:17], 0, v[124:125]
	s_waitcnt vmcnt(11)
	v_lshlrev_b32_e32 v114, 16, v232
	v_and_b32_e32 v115, 0xffff0000, v232
	v_lshlrev_b32_e32 v102, 16, v233
	v_and_b32_e32 v103, 0xffff0000, v233
	v_lshlrev_b32_e32 v126, 16, v234
	v_and_b32_e32 v127, 0xffff0000, v234
	v_lshlrev_b32_e32 v104, 16, v235
	v_and_b32_e32 v105, 0xffff0000, v235
	v_pk_mul_f32 v[128:129], v[34:35], v[102:103]
	v_pk_mul_f32 v[102:103], v[32:33], v[114:115]
	v_pk_mul_f32 v[114:115], v[30:31], v[104:105]
	v_pk_mul_f32 v[104:105], v[28:29], v[126:127]
	v_cvt_pk_bf16_f32 v102, v102, v103
	v_cvt_pk_bf16_f32 v103, v128, v129
	s_nop 0
	v_cvt_pk_bf16_f32 v104, v104, v105
	v_cvt_pk_bf16_f32 v105, v114, v115
	s_nop 0
	global_store_dwordx4 v[106:107], v[102:105], off
	s_waitcnt vmcnt(11)
	v_lshlrev_b32_e32 v106, 16, v238
	v_lshlrev_b32_e32 v102, 16, v236
	v_and_b32_e32 v103, 0xffff0000, v236
	v_lshlrev_b32_e32 v104, 16, v237
	v_and_b32_e32 v105, 0xffff0000, v237
	v_and_b32_e32 v107, 0xffff0000, v238
	v_lshlrev_b32_e32 v112, 16, v239
	v_and_b32_e32 v113, 0xffff0000, v239
	v_pk_mul_f32 v[104:105], v[10:11], v[104:105]
	v_pk_mul_f32 v[102:103], v[8:9], v[102:103]
	v_pk_mul_f32 v[112:113], v[6:7], v[112:113]
	v_pk_mul_f32 v[106:107], v[4:5], v[106:107]
	v_cvt_pk_bf16_f32 v102, v102, v103
	v_cvt_pk_bf16_f32 v103, v104, v105
	s_nop 0
	v_cvt_pk_bf16_f32 v104, v106, v107
	v_cvt_pk_bf16_f32 v105, v112, v113
	global_store_dwordx4 v[124:125], v[102:105], off
	s_cbranch_execz .LBB0_849

.LBB0_1064:
	s_ashr_i32 s15, s14, 31
	s_lshl_b64 s[20:21], s[14:15], 20
	s_add_u32 s20, s3, s20
	s_addc_u32 s21, s33, s21
	s_and_b64 s[22:23], s[30:31], exec
	s_cselect_b32 s15, s21, s27
	s_cselect_b32 s25, s20, s26
	s_ashr_i32 s17, s16, 31
	s_lshl_b64 s[22:23], s[16:17], 20
	s_add_u32 s22, s38, s22
	s_addc_u32 s23, s39, s23
	s_and_b64 s[30:31], s[30:31], exec
	s_cselect_b32 s17, s23, s29
	s_cselect_b32 s56, s22, s28
	s_add_u32 s26, s26, 0x80080
	s_addc_u32 s27, s27, 0
	s_add_u32 s57, s28, 0x100
	v_mov_b32_e32 v0, 0
	s_addc_u32 s58, s29, 0
	s_mov_b32 s59, -2
	v_mov_b32_e32 v1, v0
	v_mov_b32_e32 v2, v0
	v_mov_b32_e32 v3, v0
	v_mov_b32_e32 v4, v0
	v_mov_b32_e32 v5, v0
	v_mov_b32_e32 v6, v0
	v_mov_b32_e32 v7, v0
	v_mov_b32_e32 v16, v0
	v_mov_b32_e32 v17, v0
	v_mov_b32_e32 v18, v0
	v_mov_b32_e32 v19, v0
	v_mov_b32_e32 v20, v0
	v_mov_b32_e32 v21, v0
	v_mov_b32_e32 v22, v0
	v_mov_b32_e32 v23, v0
	v_mov_b32_e32 v32, v0
	v_mov_b32_e32 v33, v0
	v_mov_b32_e32 v34, v0
	v_mov_b32_e32 v35, v0
	v_mov_b32_e32 v36, v0
	v_mov_b32_e32 v37, v0
	v_mov_b32_e32 v38, v0
	v_mov_b32_e32 v39, v0
	v_mov_b32_e32 v48, v0
	v_mov_b32_e32 v49, v0
	v_mov_b32_e32 v50, v0
	v_mov_b32_e32 v51, v0
	v_mov_b32_e32 v52, v0
	v_mov_b32_e32 v53, v0
	v_mov_b32_e32 v54, v0
	v_mov_b32_e32 v55, v0
	v_mov_b32_e32 v8, v0
	v_mov_b32_e32 v9, v0
	v_mov_b32_e32 v10, v0
	v_mov_b32_e32 v11, v0
	v_mov_b32_e32 v12, v0
	v_mov_b32_e32 v13, v0
	v_mov_b32_e32 v14, v0
	v_mov_b32_e32 v15, v0
	v_mov_b32_e32 v24, v0
	v_mov_b32_e32 v25, v0
	v_mov_b32_e32 v26, v0
	v_mov_b32_e32 v27, v0
	v_mov_b32_e32 v28, v0
	v_mov_b32_e32 v29, v0
	v_mov_b32_e32 v30, v0
	v_mov_b32_e32 v31, v0
	v_mov_b32_e32 v40, v0
	v_mov_b32_e32 v41, v0
	v_mov_b32_e32 v42, v0
	v_mov_b32_e32 v43, v0
	v_mov_b32_e32 v44, v0
	v_mov_b32_e32 v45, v0
	v_mov_b32_e32 v46, v0
	v_mov_b32_e32 v47, v0
	v_mov_b32_e32 v56, v0
	v_mov_b32_e32 v57, v0
	v_mov_b32_e32 v58, v0
	v_mov_b32_e32 v59, v0
	v_mov_b32_e32 v60, v0
	v_mov_b32_e32 v61, v0
	v_mov_b32_e32 v62, v0
	v_mov_b32_e32 v63, v0
	v_mov_b32_e32 v64, v0
	v_mov_b32_e32 v65, v0
	v_mov_b32_e32 v66, v0
	v_mov_b32_e32 v67, v0
	v_mov_b32_e32 v68, v0
	v_mov_b32_e32 v69, v0
	v_mov_b32_e32 v70, v0
	v_mov_b32_e32 v71, v0
	v_mov_b32_e32 v80, v0
	v_mov_b32_e32 v81, v0
	v_mov_b32_e32 v82, v0
	v_mov_b32_e32 v83, v0
	v_mov_b32_e32 v84, v0
	v_mov_b32_e32 v85, v0
	v_mov_b32_e32 v86, v0
	v_mov_b32_e32 v87, v0
	v_mov_b32_e32 v96, v0
	v_mov_b32_e32 v97, v0
	v_mov_b32_e32 v98, v0
	v_mov_b32_e32 v99, v0
	v_mov_b32_e32 v100, v0
	v_mov_b32_e32 v101, v0
	v_mov_b32_e32 v102, v0
	v_mov_b32_e32 v103, v0
	v_mov_b32_e32 v112, v0
	v_mov_b32_e32 v113, v0
	v_mov_b32_e32 v114, v0
	v_mov_b32_e32 v115, v0
	v_mov_b32_e32 v116, v0
	v_mov_b32_e32 v117, v0
	v_mov_b32_e32 v118, v0
	v_mov_b32_e32 v119, v0
	v_mov_b32_e32 v72, v0
	v_mov_b32_e32 v73, v0
	v_mov_b32_e32 v74, v0
	v_mov_b32_e32 v75, v0
	v_mov_b32_e32 v76, v0
	v_mov_b32_e32 v77, v0
	v_mov_b32_e32 v78, v0
	v_mov_b32_e32 v79, v0
	v_mov_b32_e32 v88, v0
	v_mov_b32_e32 v89, v0
	v_mov_b32_e32 v90, v0
	v_mov_b32_e32 v91, v0
	v_mov_b32_e32 v92, v0
	v_mov_b32_e32 v93, v0
	v_mov_b32_e32 v94, v0
	v_mov_b32_e32 v95, v0
	v_mov_b32_e32 v104, v0
	v_mov_b32_e32 v105, v0
	v_mov_b32_e32 v106, v0
	v_mov_b32_e32 v107, v0
	v_mov_b32_e32 v108, v0
	v_mov_b32_e32 v109, v0
	v_mov_b32_e32 v110, v0
	v_mov_b32_e32 v111, v0
	v_mov_b32_e32 v120, v0
	v_mov_b32_e32 v121, v0
	v_mov_b32_e32 v122, v0
	v_mov_b32_e32 v123, v0
	v_mov_b32_e32 v124, v0
	v_mov_b32_e32 v125, v0
	v_mov_b32_e32 v126, v0
	v_mov_b32_e32 v127, v0
	.p2align 7
